# weight conversion: one touch-load per item brings the wave's next source block (expert weights) towards L2 ahead of its 8 real loads
# baseline (speedup 1.0000x reference)
; #define in KArgIn()
; template <int SEL> __global__ void __launch_bounds__(NWAVES * 64, 2) fwd_kernel(Args args) {
;     ...
;         const int gw = vcu * NWAVES + wave, NGW = G * NWAVES;
;         constexpr int I_A = 16 * 48, I_B = 16 * 112, I_BR = 8 * 32, I_O = 16 * 32, I_L = I_A + I_B + 2 * I_BR + I_O;
;         constexpr int I_GU = 16 * 176, I_DN = 44 * 32, I_EGU = 16 * 224, I_EDN = 56 * 32;
;         constexpr int NITEMS = 2 * I_L + I_GU + I_DN + 8 * I_EGU + 8 * I_EDN;
;         _Pragma("nounroll") for (int repp_ = 0; repp_ < REP_P; ++repp_)
;         for (int it = gw; it < NITEMS; it += NGW) {
;             int r = it;
;             if (r < 2 * I_L) { const int l = r / I_L; r -= l * I_L; const float* win = in[3] + (size_t)l * 1024 * NIN; bf16* wt = q_Win_t + (size_t)l * NPROJ * 1024;
;                 if (r < I_A) { tr_seg<0>(win, NIN, 1024, 0, 1536, wt, 0, 0, scr, r, lane); continue; } r -= I_A;
;                 if (r < I_B) { tr_seg<0>(win, NIN, 1024, 1544, 3584, wt, 1536, 0, scr, r, lane); continue; } r -= I_B;
;                 if (r < I_BR) { tr_seg<0>(in[10] + (size_t)l * 512 * 1024, 1024, 512, 0, 1024, q_Wbr_t + (size_t)l * 2048 * 512, 0, 0, scr, r, lane); continue; } r -= I_BR;
;                 if (r < I_BR) { tr_seg<0>(in[11] + (size_t)l * 512 * 1024, 1024, 512, 0, 1024, q_Wbr_t + (size_t)l * 2048 * 512, 1024, 0, scr, r, lane); continue; } r -= I_BR;
;                 tr_seg<0>(in[12] + (size_t)l * 1024 * 1024, 1024, 1024, 0, 1024, q_Wo_t + (size_t)l * 1024 * 1024, 0, 0, scr, r, lane); continue; }
;             r -= 2 * I_L;
;             if (r < I_GU) { if constexpr (DENSE_FP8 != 0) tr_seg8<1>(in[16], 2 * DFF, 1024, 0, 2 * DFF, (unsigned char*)q_Wgu_t, 0, DFF, W8_SCALE, scr, r, lane); else tr_seg<1>(in[16], 2 * DFF, 1024, 0, 2 * DFF, q_Wgu_t, 0, DFF, scr, r, lane); continue; } r -= I_GU;
;             if (r < I_DN) { if constexpr (DENSE_FP8 == 2) tr_seg8<0>(in[17], 1024, DFF, 0, 1024, (unsigned char*)q_Wdn_t, 0, 0, W8_SCALE, scr, r, lane); else tr_seg<0>(in[17], 1024, DFF, 0, 1024, q_Wdn_t, 0, 0, scr, r, lane); continue; } r -= I_DN;
;             if (r < 8 * I_EGU) { const int e = r / I_EGU; r -= e * I_EGU; tr_seg8<1>(in[19] + (size_t)e * 1024 * 2 * DFFE, 2 * DFFE, 1024, 0, 2 * DFFE, (unsigned char*)q_Wegu_t + (size_t)e * 2 * DFFE * 1024, 0, DFFE, W8_SCALE, scr, r, lane); continue; } r -= 8 * I_EGU;
.LBB0_7:
	s_or_b64 exec, exec, s[4:5]
	s_lshr_b32 s68, s70, 6
	s_lshl_b32 s3, s76, 3
	s_add_i32 s4, s68, s3
	s_lshl_b32 s30, s33, 3
	s_cmp_gt_i32 s4, 0xd47f
	v_mbcnt_lo_u32_b32 v2, -1, 0
	v_mbcnt_hi_u32_b32 v2, -1, v2
	s_cbranch_scc1 .LBB0_41
	s_lshl_b32 s3, s68, 14
	s_add_i32 s3, s3, 0
	v_bfe_u32 v19, v2, 3, 3
	v_and_b32_e32 v17, 7, v2
	v_lshlrev_b32_e32 v2, 2, v17
	v_lshl_add_u32 v13, v17, 4, s3
	v_lshlrev_b32_e32 v20, 3, v17
	v_mul_u32_u24_e32 v17, 0x420, v17
	v_lshlrev_b32_e32 v22, 2, v19
	v_add3_u32 v17, s3, v17, v22
	s_movk_i32 s3, 0x1c00
	v_mov_b32_e32 v24, 0x46000
	v_mad_u32_u24 v44, v19, s3, v24
	v_mov_b32_e32 v24, 0x54000
	v_mad_u32_u24 v46, v19, s3, v24
	v_mov_b32_e32 v24, 0x62000
	v_mad_u32_u24 v48, v19, s3, v24
	s_movk_i32 s3, 0x1600
	v_mov_b32_e32 v26, 0x37000
	v_mad_u32_u24 v52, v19, s3, v26
	v_mov_b32_e32 v26, 0x42000
	v_or_b32_e32 v27, 8, v19
	v_mad_u32_u24 v54, v19, s3, v26
	v_mov_b32_e32 v26, 0x4d000
	v_lshlrev_b32_e32 v6, 10, v27
	v_mad_u32_u24 v56, v19, s3, v26
	v_lshlrev_b32_e32 v28, 9, v27
	s_movk_i32 s3, 0x1408
	v_mov_b32_e32 v27, 0x32140
	v_mad_u32_u24 v36, v19, s3, v27
	v_mov_b32_e32 v27, 0x3c180
	v_mad_u32_u24 v38, v19, s3, v27
	v_mov_b32_e32 v27, 0x461c0
	v_or_b32_e32 v29, 16, v19
	v_mad_u32_u24 v40, v19, s3, v27
	s_add_i32 s3, s4, 0xffff6380
	s_add_i32 s22, s4, 0xd380
	s_lshl_b32 s4, s76, 4
	s_lshl_b32 s6, s68, 1
	v_mov_b32_e32 v3, 0
	v_lshlrev_b32_e32 v4, 10, v19
	v_lshlrev_b32_e32 v8, 10, v29
	v_or_b32_e32 v31, 24, v19
	v_mul_u32_u24_e32 v42, 0x1c00, v19
	v_mul_u32_u24_e32 v50, 0x1600, v19
	s_add_i32 s23, s4, s6
	s_lshl_b32 s4, s76, 8
	s_lshl_b32 s6, s68, 5
	s_mov_b32 s5, 0
	v_mov_b32_e32 v5, v3
	v_mov_b32_e32 v7, v3
	v_mov_b32_e32 v9, v3
	v_lshlrev_b32_e32 v10, 10, v31
	v_mov_b32_e32 v11, v3
	v_or_b32_e32 v12, 0x8000, v4
	v_or_b32_e32 v14, 0xa000, v4
	v_or_b32_e32 v16, 0xc000, v4
	v_or_b32_e32 v18, 0xe000, v4
	v_mul_u32_u24_e32 v15, 0x84, v19
	v_mov_b32_e32 v21, v3
	v_mul_u32_u24_e32 v22, 0xe00, v19
	v_mov_b32_e32 v23, v3
	v_mul_u32_u24_e32 v24, 0xb00, v19
	v_mov_b32_e32 v25, v3
	v_lshlrev_b32_e32 v26, 9, v19
	v_lshlrev_b32_e32 v30, 9, v29
	v_lshlrev_b32_e32 v32, 9, v31
	v_mul_u32_u24_e32 v34, 0x1408, v19
	v_lshlrev_b32_e32 v2, 2, v2
	s_lshl_b32 s26, s33, 4
	s_add_i32 s27, s4, s6
	s_lshl_b32 s28, s33, 8
	s_mov_b32 s29, 0xad00000
	s_mov_b32 s31, 0xad07000
	s_mov_b32 s34, 0xad0e000
	v_lshlrev_b32_e32 v42, 2, v42
	s_mov_b32 s35, 0x38000
	s_mov_b32 s36, 0x70000
	s_mov_b32 s37, 0xa8000
	s_mov_b32 s38, 0xe0000
	v_lshlrev_b32_e32 v44, 2, v44
	v_lshlrev_b32_e32 v46, 2, v46
	v_lshlrev_b32_e32 v48, 2, v48
	s_mov_b64 s[6:7], 0x3d00000
	s_mov_b32 s39, 0x3700000
	s_mov_b32 s40, 0x3705000
	s_mov_b32 s41, 0x370b000
	v_lshlrev_b32_e32 v50, 2, v50
	s_mov_b32 s42, 0x2c000
	s_mov_b32 s43, 0x58000
	s_mov_b32 s44, 0x84000
	s_mov_b32 s45, 0xb0000
	v_lshlrev_b32_e32 v52, 2, v52
	v_lshlrev_b32_e32 v54, 2, v54
	v_lshlrev_b32_e32 v56, 2, v56
	s_mov_b64 s[8:9], 0x2c00000
	s_mov_b64 s[10:11], 0x2800000
	s_movk_i32 s46, 0x7fff
	s_mov_b32 s47, 0xffff0000
	s_mov_b64 s[12:13], 0x2500000
	s_mov_b64 s[14:15], 0x2400000
	s_mov_b64 s[16:17], 0x1820
	s_mov_b32 s48, 0x28000
	s_mov_b32 s49, 0x50000
	s_mov_b32 s50, 0x78000
	s_mov_b32 s51, 0xa0000
	v_lshlrev_b32_e32 v58, 2, v4
	v_lshlrev_b32_e32 v60, 2, v6
	v_lshlrev_b32_e32 v62, 2, v8
	v_mbcnt_lo_u32_b32 v248, -1, 0
	v_mbcnt_hi_u32_b32 v248, -1, v248
	v_lshlrev_b32_e32 v249, 12, v248
	v_mul_u32_u24_e32 v248, 0x7000, v248
	s_branch .LBB0_10

; #define in KArgIn()
; template <int SEL> __global__ void __launch_bounds__(NWAVES * 64, 2) fwd_kernel(Args args) {
;     ...
;             if (r < 8 * I_EGU) { const int e = r / I_EGU; r -= e * I_EGU; tr_seg8<1>(in[19] + (size_t)e * 1024 * 2 * DFFE, 2 * DFFE, 1024, 0, 2 * DFFE, (unsigned char*)q_Wegu_t + (size_t)e * 2 * DFFE * 1024, 0, DFFE, W8_SCALE, scr, r, lane); continue; } r -= 8 * I_EGU;
;             { const int e = r / I_EDN; r -= e * I_EDN; tr_seg8<0>(in[20] + (size_t)e * DFFE * 1024, 1024, DFFE, 0, 1024, (unsigned char*)q_Wedn_t + (size_t)e * 1024 * DFFE, 0, 0, W8_SCALE, scr, r, lane); }
.LBB0_10:
	s_add_i32 s62, s3, s30
	s_cmp_lt_i32 s62, 0
	s_cbranch_scc1 .Lp0pf_gu
	s_cmpk_ge_i32 s62, 0x3800
	s_cbranch_scc1 .Lp0pf_skip
	s_mul_hi_u32 s64, s62, 2396746
	s_mul_i32 s65, s64, 0x700
	s_sub_i32 s65, s62, s65
	s_lshr_b32 s66, s65, 5
	s_and_b32 s65, s65, 31
	s_mul_i32 s64, s64, 0xe00000
	s_lshl_b32 s66, s66, 18
	s_lshl_b32 s65, s65, 7
	s_add_i32 s64, s64, s66
	s_add_i32 s64, s64, s65
	s_load_dwordx2 s[66:67], s[0:1], 0xa0
	s_waitcnt lgkmcnt(0)
	s_add_u32 s66, s66, s64
	s_addc_u32 s67, s67, 0
	global_load_dword v250, v249, s[66:67]
	s_branch .Lp0pf_skip
.Lp0pf_gu:
	s_add_i32 s63, s62, 0x7000
	s_cmp_lt_i32 s63, 0
	s_cbranch_scc1 .Lp0pf_skip
	s_mul_hi_u32 s64, s63, 1198373
	s_mul_i32 s65, s64, 0xe00
	s_sub_i32 s65, s63, s65
	s_mul_hi_u32 s66, s65, 19173962
	s_mul_i32 s67, s66, 0xe0
	s_sub_i32 s65, s65, s67
	s_mul_i32 s64, s64, 0x1c00000
	s_mul_i32 s66, s66, 0x1c0000
	s_lshl_b32 s65, s65, 7
	s_add_i32 s64, s64, s66
	s_add_i32 s64, s64, s65
	s_load_dwordx2 s[66:67], s[0:1], 0x98
	s_waitcnt lgkmcnt(0)
	s_add_u32 s66, s66, s64
	s_addc_u32 s67, s67, 0
	global_load_dword v250, v248, s[66:67]
